# M2 scan step: next U/v tile fetched as 2 dwordx4 per thread, staged in free LDS and refilled with ds_read_u16_d16_hi, instead of 16 two-byte global loads per thread per step (on top of v022)
# speedup vs baseline: 1.0029x; 1.0029x over previous
.LBB0_1032:
	s_bitcmp1_b32 s61, 0
	s_cselect_b32 s4, 0xf600, 0
	s_cselect_b32 s101, 0x4400, 0
	s_add_i32 s101, s101, 0x1ec00
	s_add_i32 s65, s4, 0
	v_and_b32_e32 v80, 3, v201
	v_lshlrev_b32_e32 v80, 3, v80
	v_mov_b32_e32 v81, 0xf8e81000
	v_lshrrev_b32_e32 v80, v80, v81
	v_bfe_i32 v80, v80, 0, 8
	v_lshl_add_u32 v86, v208, 1, s101
	v_lshl_add_u32 v87, v154, 1, v86
	v_lshl_add_u32 v86, v215, 1, v86
	v_lshl_add_u32 v77, v208, 1, s65
	v_lshl_add_u32 v78, v209, 1, s65
	v_lshl_add_u32 v76, v154, 1, v77
	v_add_u32_e32 v76, v76, v80
	v_add_u32_e32 v84, 0x4400, v76
	v_lshl_add_u32 v79, v109, 1, v78
	v_add_u32_e32 v79, v79, v80
	v_add_u32_e32 v82, 0x8800, v79
	s_mov_b64 s[4:5], -1
	s_and_b64 vcc, exec, s[40:41]
	v_lshl_add_u32 v77, v215, 1, v77
	v_add_u32_e32 v77, v77, v80
	v_add_u32_e32 v85, 0x4400, v77
	v_lshl_add_u32 v78, v216, 1, v78
	v_add_u32_e32 v78, v78, v80
	v_add_u32_e32 v83, 0x8800, v78
	s_waitcnt vmcnt(21)
	ds_write2_b64 v76, v[32:33], v[34:35] offset1:2
	s_waitcnt vmcnt(20)
	ds_write2_b64 v82, v[36:37], v[38:39] offset1:2
	s_cbranch_vccz .LBB0_1034
	s_waitcnt vmcnt(19)
	ds_write2_b64 v77, v[40:41], v[42:43] offset1:2
	s_waitcnt vmcnt(18)
	ds_write2_b64 v83, v[44:45], v[46:47] offset1:2
	s_mov_b64 s[4:5], 0

.LBB0_1036:
	s_cmp_eq_u32 s61, 0
	s_cbranch_scc1 .Lm2_nou_a
	ds_write_b128 v87, v[184:187]
	ds_write_b128 v86, v[188:191]

.LBB0_1043:
	s_ashr_i32 s87, s86, 31
	s_lshl_b64 s[70:71], s[86:87], 14
	s_lshl_b64 s[68:69], s[86:87], 13
	v_lshl_add_u64 v[40:41], v[166:167], 0, s[70:71]
	v_lshl_add_u64 v[42:43], v[172:173], 0, s[70:71]
	v_lshl_add_u64 v[32:33], v[116:117], 1, v[40:41]
	v_lshl_add_u64 v[36:37], v[118:119], 1, v[42:43]
	v_lshl_add_u64 v[40:41], v[120:121], 1, v[40:41]
	v_lshl_add_u64 v[44:45], v[122:123], 1, v[42:43]
	v_lshl_add_u64 v[48:49], v[174:175], 0, s[68:69]
	s_lshl_b64 s[68:69], s[86:87], 9
	global_load_dwordx4 v[32:35], v[32:33], off
	s_nop 0
	global_load_dwordx4 v[36:39], v[36:37], off
	s_nop 0
	global_load_dwordx4 v[40:43], v[40:41], off
	s_nop 0
	global_load_dwordx4 v[44:47], v[44:45], off
	v_lshl_add_u64 v[76:77], v[176:177], 0, s[68:69]
	global_load_dwordx4 v[48:51], v[48:49], off
	s_nop 0
	global_load_dword v210, v[76:77], off
	s_mov_b64 s[86:87], -1
	s_and_b64 vcc, exec, s[40:41]
	s_cbranch_vccz .LBB0_1045
	s_and_b64 s[68:69], s[4:5], exec
	v_add_u32_e32 v76, 64, v211
	s_cselect_b32 s67, 64, 32
	v_cndmask_b32_e64 v92, v142, v76, s[4:5]
	s_add_i32 s4, s67, -1
	v_min_i32_e32 v76, s4, v200
	v_add_u32_e32 v78, v76, v92
	v_lshrrev_b32_e32 v76, 8, v78
	v_lshlrev_b32_e32 v78, 9, v78
	v_mul_i32_i24_e32 v76, 60, v76
	v_and_b32_e32 v100, 0x1fe00, v78
	v_ashrrev_i32_e32 v77, 31, v76
	v_lshlrev_b64 v[76:77], 17, v[76:77]
	v_lshl_add_u64 v[76:77], s[10:11], 0, v[76:77]
	v_lshl_add_u64 v[76:77], v[76:77], 0, v[100:101]
	v_lshl_add_u64 v[76:77], v[76:77], 0, v[128:129]
	v_lshl_add_u64 v[76:77], v[76:77], 0, v[170:171]
	v_lshrrev_b32_e32 v78, 4, v201
	v_lshlrev_b32_e32 v78, 9, v78
	v_and_b32_e32 v79, 15, v201
	v_lshl_add_u32 v78, v79, 4, v78
	v_lshlrev_b32_e32 v80, 9, v200
	v_sub_u32_e32 v78, v78, v80
	v_lshrrev_b32_e32 v80, 6, v201
	v_lshl_or_b32 v80, v80, 4, v79
	v_lshlrev_b32_e32 v80, 1, v80
	v_sub_u32_e32 v78, v78, v80
	v_ashrrev_i32_e32 v79, 31, v78
	v_lshl_add_u64 v[76:77], v[76:77], 0, v[78:79]
	s_mov_b64 s[68:69], 0x4000
	v_lshl_add_u64 v[78:79], v[76:77], 0, s[68:69]
	global_load_dwordx4 v[184:187], v[76:77], off
	global_load_dwordx4 v[188:191], v[78:79], off
	s_mov_b64 s[86:87], 0
.LBB0_1045:
	s_andn2_b64 vcc, exec, s[86:87]
	s_cbranch_vccnz .LBB0_1048
	s_ashr_i32 s85, s84, 31
	s_lshl_b64 s[4:5], s[84:85], 14
	v_lshl_add_u64 v[52:53], v[168:169], 0, s[4:5]
	s_add_u32 s4, s52, s4
	s_addc_u32 s5, s53, s5
	v_lshl_add_u64 v[54:55], v[116:117], 1, v[52:53]
	s_waitcnt vmcnt(22)
	v_lshl_add_u64 v[56:57], v[120:121], 1, v[52:53]
	v_lshlrev_b32_e32 v80, 1, v208
	v_mov_b32_e32 v81, 0
	v_lshl_add_u64 v[76:77], v[116:117], 1, s[4:5]
	v_lshl_add_u64 v[78:79], v[120:121], 1, s[4:5]
	v_lshl_add_u64 v[76:77], v[76:77], 0, v[80:81]
	v_lshl_add_u64 v[78:79], v[78:79], 0, v[80:81]
	global_load_dwordx4 v[184:187], v[76:77], off
	global_load_dwordx4 v[188:191], v[78:79], off
	s_nop 0
	global_load_dwordx4 v[52:55], v[54:55], off
	s_nop 0
	global_load_dwordx4 v[56:59], v[56:57], off
	s_branch .LBB0_1048

.LBB0_1048:
	s_and_b64 vcc, exec, s[40:41]
	s_cmp_eq_u32 s61, 1
	s_cbranch_scc1 .Lm2_norefill_a
	v_mul_u32_u24_e32 v100, 0x110, v200
	v_lshrrev_b32_e32 v222, 6, v201
	v_and_b32_e32 v238, 15, v201
	v_lshl_or_b32 v222, v222, 4, v238
	v_lshl_add_u32 v100, v222, 1, v100
	v_add_u32_e32 v100, s101, v100
	v_mov_b32_e32 v60, 0
	v_mov_b32_e32 v61, 0
	v_mov_b32_e32 v62, 0
	v_mov_b32_e32 v63, 0
	v_mov_b32_e32 v64, 0
	v_mov_b32_e32 v65, 0
	v_mov_b32_e32 v66, 0
	v_mov_b32_e32 v67, 0
	v_mov_b32_e32 v68, 0
	v_mov_b32_e32 v69, 0
	v_mov_b32_e32 v70, 0
	v_mov_b32_e32 v71, 0
	v_mov_b32_e32 v72, 0
	v_mov_b32_e32 v73, 0
	v_mov_b32_e32 v74, 0
	v_mov_b32_e32 v75, 0
	ds_read_u16_d16_hi v68, v100
	ds_read_u16_d16_hi v69, v100 offset:272
	ds_read_u16_d16_hi v70, v100 offset:544
	ds_read_u16_d16_hi v71, v100 offset:816
	ds_read_u16_d16_hi v72, v100 offset:4352
	ds_read_u16_d16_hi v73, v100 offset:4624
	ds_read_u16_d16_hi v74, v100 offset:4896
	ds_read_u16_d16_hi v75, v100 offset:5168
	ds_read_u16_d16_hi v60, v100 offset:8704
	ds_read_u16_d16_hi v61, v100 offset:8976
	ds_read_u16_d16_hi v62, v100 offset:9248
	ds_read_u16_d16_hi v63, v100 offset:9520
	ds_read_u16_d16_hi v64, v100 offset:13056
	ds_read_u16_d16_hi v65, v100 offset:13328
	ds_read_u16_d16_hi v66, v100 offset:13600
	ds_read_u16_d16_hi v67, v100 offset:13872
.Lm2_norefill_a:
	v_cvt_pk_bf16_f32 v84, v0, v1
	v_cvt_pk_bf16_f32 v85, v2, v3
	v_cvt_pk_bf16_f32 v86, v4, v5
	v_cvt_pk_bf16_f32 v87, v6, v7
	v_cvt_pk_bf16_f32 v88, v8, v9
	v_cvt_pk_bf16_f32 v89, v10, v11
	v_cvt_pk_bf16_f32 v90, v12, v13
	v_cvt_pk_bf16_f32 v91, v14, v15
	v_cvt_pk_bf16_f32 v92, v16, v17
	v_cvt_pk_bf16_f32 v93, v18, v19
	v_cvt_pk_bf16_f32 v94, v20, v21
	v_cvt_pk_bf16_f32 v95, v22, v23
	v_cvt_pk_bf16_f32 v96, v24, v25
	v_cvt_pk_bf16_f32 v97, v26, v27
	v_cvt_pk_bf16_f32 v98, v28, v29
	v_cvt_pk_bf16_f32 v99, v30, v31
	s_waitcnt lgkmcnt(0)
	s_cbranch_vccz .LBB0_1050
	v_cvt_pk_bf16_f32 v76, v68, v69
	v_cvt_pk_bf16_f32 v77, v70, v71
	v_cvt_pk_bf16_f32 v78, v72, v73
	v_cvt_pk_bf16_f32 v79, v74, v75
	v_cvt_pk_bf16_f32 v80, v60, v61
	v_cvt_pk_bf16_f32 v81, v62, v63
	v_cvt_pk_bf16_f32 v82, v64, v65
	v_cvt_pk_bf16_f32 v83, v66, v67
	s_cbranch_execz .LBB0_1051
	s_branch .LBB0_1052

.LBB0_1052:
	v_lshl_add_u32 v252, v200, 2, s65
	v_lshl_add_u32 v226, v113, 1, v252
	v_add_u32_e32 v218, v226, v213
	v_add_u32_e32 v222, 0xd000, v218
	v_add_u32_e32 v238, 0x1000, v226
	s_nop 0
	ds_read_b128 v[60:63], v226
	s_nop 0
	ds_read_b128 v[64:67], v226 offset:64
	ds_read_b128 v[68:71], v226 offset:128
	ds_read_b128 v[72:75], v226 offset:192
	ds_read_b128 v[218:221], v222
	ds_read_b128 v[222:225], v222 offset:64
	ds_read_b128 v[226:229], v238 offset:256
	ds_read_b128 v[230:233], v238 offset:320
	ds_read_b128 v[234:237], v238 offset:384
	ds_read_b128 v[238:241], v238 offset:448
	v_add_u32_e32 v253, v252, v115
	v_add_u32_e32 v246, 0xd000, v253
	ds_read_b128 v[242:245], v246
	ds_read_b128 v[246:249], v246 offset:64
	s_cmpk_lt_i32 s66, 0x80
	v_subrev_u32_e32 v100, 32, v142
	s_cselect_b64 vcc, -1, 0
	v_cndmask_b32_e32 v100, v100, v211, vcc
	v_or_b32_e32 v250, v100, v200
	s_waitcnt lgkmcnt(11)
	v_mfma_f32_16x16x32_bf16 v[60:63], v[60:63], v[84:87], 0
	v_ashrrev_i32_e32 v251, 31, v250
	s_waitcnt lgkmcnt(10)
	v_mfma_f32_16x16x32_bf16 v[60:63], v[64:67], v[88:91], v[60:63]
	v_lshlrev_b64 v[64:65], 14, v[250:251]
	s_waitcnt lgkmcnt(9)
	v_mfma_f32_16x16x32_bf16 v[60:63], v[68:71], v[92:95], v[60:63]
	v_lshl_add_u64 v[68:69], v[182:183], 0, v[64:65]
	v_add_co_u32_e64 v70, s[4:5], s56, v68
	s_waitcnt lgkmcnt(5)
	v_mfma_f32_16x16x32_bf16 v[226:229], v[226:229], v[84:87], 0
	v_addc_co_u32_e64 v71, s[4:5], 0, v69, s[4:5]
	v_mfma_f32_16x16x32_bf16 v[60:63], v[72:75], v[96:99], v[60:63]
	v_mfma_f32_16x16x32_bf16 v[60:63], v[218:221], v[76:79], v[60:63]
	s_waitcnt lgkmcnt(4)
	v_mfma_f32_16x16x32_bf16 v[64:67], v[230:233], v[88:91], v[226:229]
	v_mfma_f32_16x16x32_bf16 v[60:63], v[222:225], v[80:83], v[60:63]
	s_waitcnt lgkmcnt(3)
	v_mfma_f32_16x16x32_bf16 v[64:67], v[234:237], v[92:95], v[64:67]
	s_waitcnt lgkmcnt(2)
	v_mfma_f32_16x16x32_bf16 v[64:67], v[238:241], v[96:99], v[64:67]
	s_nop 3
	global_store_dword v[68:69], v60, off
	v_add_co_u32_e64 v60, s[4:5], s57, v68
	global_store_dword v[70:71], v61, off
	s_nop 0
	v_addc_co_u32_e64 v61, s[4:5], 0, v69, s[4:5]
	global_store_dword v[60:61], v62, off
	v_add_co_u32_e64 v60, s[4:5], s58, v68
	v_or_b32_e32 v68, 16, v250
	s_nop 0
	v_addc_co_u32_e64 v61, s[4:5], 0, v69, s[4:5]
	global_store_dword v[60:61], v63, off
	s_waitcnt lgkmcnt(1)
	v_mfma_f32_16x16x32_bf16 v[60:63], v[242:245], v[76:79], v[64:67]
	v_ashrrev_i32_e32 v69, 31, v68
	s_nop 1
	v_lshlrev_b64 v[64:65], 14, v[68:69]
	s_waitcnt lgkmcnt(0)
	v_mfma_f32_16x16x32_bf16 v[60:63], v[246:249], v[80:83], v[60:63]
	v_lshl_add_u64 v[64:65], v[182:183], 0, v[64:65]
	v_add_co_u32_e64 v66, s[4:5], s56, v64
	s_nop 1
	v_addc_co_u32_e64 v67, s[4:5], 0, v65, s[4:5]
	s_nop 2
	global_store_dword v[64:65], v60, off
	v_add_co_u32_e64 v60, s[4:5], s57, v64
	global_store_dword v[66:67], v61, off
	s_nop 0
	v_addc_co_u32_e64 v61, s[4:5], 0, v65, s[4:5]
	global_store_dword v[60:61], v62, off
	v_add_co_u32_e64 v60, s[4:5], s58, v64
	s_nop 1
	v_addc_co_u32_e64 v61, s[4:5], 0, v65, s[4:5]
	global_store_dword v[60:61], v63, off
	v_add_u32_e32 v100, v252, v212
	v_add_u32_e32 v218, v100, v217
	ds_read_b128 v[60:63], v100
	ds_read_b128 v[64:67], v100 offset:64
	ds_read_b128 v[68:71], v100 offset:128
	ds_read_b128 v[72:75], v100 offset:192
	v_add_u32_e32 v222, 0xd000, v218
	v_add_u32_e32 v100, 0x1000, v100
	ds_read_b128 v[218:221], v222
	ds_read_b128 v[222:225], v222 offset:64
	ds_read_b128 v[226:229], v100 offset:256
	ds_read_b128 v[230:233], v100 offset:320
	ds_read_b128 v[234:237], v100 offset:384
	ds_read_b128 v[238:241], v100 offset:448
	v_add_u32_e32 v100, 0xe000, v253
	ds_read_b128 v[242:245], v100 offset:512
	ds_read_b128 v[246:249], v100 offset:576
	s_waitcnt lgkmcnt(11)
	v_mfma_f32_16x16x32_bf16 v[60:63], v[60:63], v[84:87], 0
	s_waitcnt lgkmcnt(10)
	v_mfma_f32_16x16x32_bf16 v[60:63], v[64:67], v[88:91], v[60:63]
	v_add_u32_e32 v64, 32, v250
	v_ashrrev_i32_e32 v65, 31, v64
	v_lshlrev_b64 v[64:65], 14, v[64:65]
	s_waitcnt lgkmcnt(9)
	v_mfma_f32_16x16x32_bf16 v[60:63], v[68:71], v[92:95], v[60:63]
	v_lshl_add_u64 v[64:65], v[182:183], 0, v[64:65]
	v_cndmask_b32_e32 v69, v179, v65, vcc
	v_cndmask_b32_e32 v68, v178, v64, vcc
	s_waitcnt lgkmcnt(8)
	v_mfma_f32_16x16x32_bf16 v[60:63], v[72:75], v[96:99], v[60:63]
	v_add_co_u32_e64 v70, s[4:5], s56, v68
	s_waitcnt lgkmcnt(7)
	v_mfma_f32_16x16x32_bf16 v[60:63], v[218:221], v[76:79], v[60:63]
	v_addc_co_u32_e64 v71, s[4:5], 0, v69, s[4:5]
	s_waitcnt lgkmcnt(5)
	v_mfma_f32_16x16x32_bf16 v[64:67], v[226:229], v[84:87], 0
	v_mfma_f32_16x16x32_bf16 v[60:63], v[222:225], v[80:83], v[60:63]
	s_waitcnt lgkmcnt(4)
	v_mfma_f32_16x16x32_bf16 v[64:67], v[230:233], v[88:91], v[64:67]
	s_waitcnt lgkmcnt(3)
	v_mfma_f32_16x16x32_bf16 v[64:67], v[234:237], v[92:95], v[64:67]
	s_nop 3
	global_store_dword v[68:69], v60, off
	v_add_co_u32_e64 v60, s[4:5], s57, v68
	global_store_dword v[70:71], v61, off
	s_nop 0
	v_addc_co_u32_e64 v61, s[4:5], 0, v69, s[4:5]
	global_store_dword v[60:61], v62, off
	v_add_co_u32_e64 v60, s[4:5], s58, v68
	s_nop 1
	v_addc_co_u32_e64 v61, s[4:5], 0, v69, s[4:5]
	global_store_dword v[60:61], v63, off
	s_waitcnt lgkmcnt(2)
	v_mfma_f32_16x16x32_bf16 v[60:63], v[238:241], v[96:99], v[64:67]
	s_waitcnt lgkmcnt(1)
	v_mfma_f32_16x16x32_bf16 v[60:63], v[242:245], v[76:79], v[60:63]
	s_nop 0
	v_add_u32_e32 v64, 48, v250
	v_ashrrev_i32_e32 v65, 31, v64
	v_lshlrev_b64 v[64:65], 14, v[64:65]
	v_lshl_add_u64 v[64:65], v[182:183], 0, v[64:65]
	s_waitcnt lgkmcnt(0)
	v_mfma_f32_16x16x32_bf16 v[60:63], v[246:249], v[80:83], v[60:63]
	v_cndmask_b32_e32 v64, v180, v64, vcc
	v_cndmask_b32_e32 v65, v181, v65, vcc
	v_add_co_u32_e32 v66, vcc, s56, v64
	s_nop 1
	v_addc_co_u32_e32 v67, vcc, 0, v65, vcc
	s_nop 1
	global_store_dword v[64:65], v60, off
	v_add_co_u32_e32 v60, vcc, s57, v64
	global_store_dword v[66:67], v61, off
	s_nop 0
	v_addc_co_u32_e32 v61, vcc, 0, v65, vcc
	global_store_dword v[60:61], v62, off
	v_add_co_u32_e32 v60, vcc, s58, v64
	s_nop 1
	v_addc_co_u32_e32 v61, vcc, 0, v65, vcc
	global_store_dword v[60:61], v63, off
	v_lshl_add_u32 v100, v200, 2, s65
	v_add_u32_e32 v234, v100, v103
	v_add_u32_e32 v64, 0x8800, v234
	v_add_u32_e32 v88, 0x9000, v234
	v_add_u32_e32 v96, 0x9800, v234
	ds_read_b128 v[60:63], v64
	ds_read_b128 v[64:67], v64 offset:64
	ds_read_b128 v[68:71], v100 offset:62464
	ds_read_b128 v[72:75], v100 offset:62528
	ds_read_b128 v[84:87], v88 offset:256
	ds_read_b128 v[88:91], v88 offset:320
	ds_read_b128 v[92:95], v96 offset:512
	ds_read_b128 v[96:99], v96 offset:576
	ds_read_b128 v[218:221], v100 offset:62592
	ds_read_b128 v[222:225], v100 offset:62656
	v_add_u32_e32 v230, 0xa000, v234
	ds_read_b128 v[226:229], v230 offset:768
	ds_read_b128 v[230:233], v230 offset:832
	s_waitcnt lgkmcnt(9)
	v_pk_mul_f32 v[2:3], v[2:3], v[70:71]
	v_pk_mul_f32 v[0:1], v[0:1], v[68:69]
	s_waitcnt lgkmcnt(8)
	v_pk_mul_f32 v[6:7], v[6:7], v[74:75]
	v_pk_mul_f32 v[4:5], v[4:5], v[72:73]
	s_waitcnt lgkmcnt(3)
	v_pk_mul_f32 v[10:11], v[10:11], v[220:221]
	v_pk_mul_f32 v[8:9], v[8:9], v[218:219]
	s_waitcnt lgkmcnt(2)
	v_pk_mul_f32 v[14:15], v[14:15], v[224:225]
	v_pk_mul_f32 v[12:13], v[12:13], v[222:223]
	v_mfma_f32_16x16x32_bf16 v[0:3], v[60:63], v[76:79], v[0:3]
	v_mfma_f32_16x16x32_bf16 v[4:7], v[84:87], v[76:79], v[4:7]
	v_mfma_f32_16x16x32_bf16 v[8:11], v[92:95], v[76:79], v[8:11]
	s_waitcnt lgkmcnt(1)
	v_mfma_f32_16x16x32_bf16 v[12:15], v[226:229], v[76:79], v[12:15]
	v_mfma_f32_16x16x32_bf16 v[0:3], v[64:67], v[80:83], v[0:3]
	v_mfma_f32_16x16x32_bf16 v[4:7], v[88:91], v[80:83], v[4:7]
	v_mfma_f32_16x16x32_bf16 v[8:11], v[96:99], v[80:83], v[8:11]
	s_waitcnt lgkmcnt(0)
	v_mfma_f32_16x16x32_bf16 v[12:15], v[230:233], v[80:83], v[12:15]
	v_add_u32_e32 v64, 0xa800, v234
	v_add_u32_e32 v88, 0xb000, v234
	v_add_u32_e32 v96, 0xb800, v234
	ds_read_b128 v[60:63], v64 offset:1024
	ds_read_b128 v[64:67], v64 offset:1088
	ds_read_b128 v[68:71], v100 offset:62720
	ds_read_b128 v[72:75], v100 offset:62784
	ds_read_b128 v[84:87], v88 offset:1280
	ds_read_b128 v[88:91], v88 offset:1344
	ds_read_b128 v[92:95], v96 offset:1536
	ds_read_b128 v[96:99], v96 offset:1600
	ds_read_b128 v[218:221], v100 offset:62848
	ds_read_b128 v[222:225], v100 offset:62912
	v_add_u32_e32 v100, 0xc000, v234
	ds_read_b128 v[226:229], v100 offset:1792
	ds_read_b128 v[230:233], v100 offset:1856
	s_waitcnt lgkmcnt(9)
	v_pk_mul_f32 v[18:19], v[18:19], v[70:71]
	v_pk_mul_f32 v[16:17], v[16:17], v[68:69]
	s_waitcnt lgkmcnt(8)
	v_pk_mul_f32 v[22:23], v[22:23], v[74:75]
	v_pk_mul_f32 v[20:21], v[20:21], v[72:73]
	s_waitcnt lgkmcnt(3)
	v_pk_mul_f32 v[26:27], v[26:27], v[220:221]
	v_pk_mul_f32 v[24:25], v[24:25], v[218:219]
	s_waitcnt lgkmcnt(2)
	v_pk_mul_f32 v[30:31], v[30:31], v[224:225]
	v_pk_mul_f32 v[28:29], v[28:29], v[222:223]
	v_mfma_f32_16x16x32_bf16 v[16:19], v[60:63], v[76:79], v[16:19]
	v_mfma_f32_16x16x32_bf16 v[20:23], v[84:87], v[76:79], v[20:23]
	v_mfma_f32_16x16x32_bf16 v[24:27], v[92:95], v[76:79], v[24:27]
	s_waitcnt lgkmcnt(1)
	v_mfma_f32_16x16x32_bf16 v[28:31], v[226:229], v[76:79], v[28:31]
	v_mfma_f32_16x16x32_bf16 v[16:19], v[64:67], v[80:83], v[16:19]
	v_mfma_f32_16x16x32_bf16 v[20:23], v[88:91], v[80:83], v[20:23]
	v_mfma_f32_16x16x32_bf16 v[24:27], v[96:99], v[80:83], v[24:27]
	s_waitcnt lgkmcnt(0)
	v_mfma_f32_16x16x32_bf16 v[28:31], v[230:233], v[80:83], v[28:31]
	s_add_i32 s64, s64, 16
	s_add_i32 s22, s22, 28
	v_add_u32_e32 v142, 32, v142
	s_cmp_lg_u32 s62, s61
	v_add_u32_e32 v211, 64, v211
	s_cbranch_scc0 .LBB0_945
	s_waitcnt vmcnt(16)
	s_branch .LBB0_1032

.LBB0_2604:
	s_bitcmp1_b32 s50, 0
	s_cselect_b32 s4, 0xf600, 0
	s_cselect_b32 s101, 0x4400, 0
	s_add_i32 s101, s101, 0x1ec00
	s_add_i32 s63, s4, 0
	v_and_b32_e32 v80, 3, v201
	v_lshlrev_b32_e32 v80, 3, v80
	v_mov_b32_e32 v81, 0xf8e81000
	v_lshrrev_b32_e32 v80, v80, v81
	v_bfe_i32 v80, v80, 0, 8
	v_lshl_add_u32 v86, v208, 1, s101
	v_lshl_add_u32 v87, v140, 1, v86
	v_lshl_add_u32 v86, v215, 1, v86
	v_lshl_add_u32 v77, v208, 1, s63
	v_lshl_add_u32 v78, v209, 1, s63
	v_lshl_add_u32 v76, v140, 1, v77
	v_add_u32_e32 v76, v76, v80
	v_add_u32_e32 v84, 0x4400, v76
	v_lshl_add_u32 v79, v109, 1, v78
	v_add_u32_e32 v79, v79, v80
	v_add_u32_e32 v82, 0x8800, v79
	s_mov_b64 s[4:5], -1
	s_and_b64 vcc, exec, s[42:43]
	v_lshl_add_u32 v77, v215, 1, v77
	v_add_u32_e32 v77, v77, v80
	v_add_u32_e32 v85, 0x4400, v77
	v_lshl_add_u32 v78, v216, 1, v78
	v_add_u32_e32 v78, v78, v80
	v_add_u32_e32 v83, 0x8800, v78
	s_waitcnt vmcnt(21)
	ds_write2_b64 v76, v[32:33], v[34:35] offset1:2
	s_waitcnt vmcnt(20)
	ds_write2_b64 v82, v[36:37], v[38:39] offset1:2
	s_cbranch_vccz .LBB0_2606
	s_waitcnt vmcnt(19)
	ds_write2_b64 v77, v[40:41], v[42:43] offset1:2
	s_waitcnt vmcnt(18)
	ds_write2_b64 v83, v[44:45], v[46:47] offset1:2
	s_mov_b64 s[4:5], 0

.LBB0_2608:
	s_cmp_eq_u32 s50, 0
	s_cbranch_scc1 .Lm2_nou_b
	ds_write_b128 v87, v[184:187]
	ds_write_b128 v86, v[188:191]

.LBB0_2615:
	s_ashr_i32 s49, s48, 31
	s_lshl_b64 s[68:69], s[48:49], 14
	s_lshl_b64 s[66:67], s[48:49], 13
	v_lshl_add_u64 v[40:41], v[166:167], 0, s[68:69]
	v_lshl_add_u64 v[42:43], v[172:173], 0, s[68:69]
	v_lshl_add_u64 v[32:33], v[116:117], 1, v[40:41]
	v_lshl_add_u64 v[36:37], v[118:119], 1, v[42:43]
	v_lshl_add_u64 v[40:41], v[120:121], 1, v[40:41]
	v_lshl_add_u64 v[44:45], v[122:123], 1, v[42:43]
	v_lshl_add_u64 v[48:49], v[174:175], 0, s[66:67]
	s_lshl_b64 s[48:49], s[48:49], 9
	global_load_dwordx4 v[32:35], v[32:33], off
	s_nop 0
	global_load_dwordx4 v[36:39], v[36:37], off
	s_nop 0
	global_load_dwordx4 v[40:43], v[40:41], off
	s_nop 0
	global_load_dwordx4 v[44:47], v[44:45], off
	v_lshl_add_u64 v[76:77], v[176:177], 0, s[48:49]
	global_load_dwordx4 v[48:51], v[48:49], off
	s_nop 0
	global_load_dword v210, v[76:77], off
	s_mov_b64 s[48:49], -1
	s_and_b64 vcc, exec, s[42:43]
	s_cbranch_vccz .LBB0_2617
	s_and_b64 s[48:49], s[4:5], exec
	v_add_u32_e32 v76, 64, v211
	s_cselect_b32 s45, 64, 32
	v_cndmask_b32_e64 v92, v126, v76, s[4:5]
	s_add_i32 s4, s45, -1
	v_min_i32_e32 v76, s4, v200
	v_add_u32_e32 v78, v76, v92
	v_lshrrev_b32_e32 v76, 8, v78
	v_lshlrev_b32_e32 v78, 9, v78
	v_mul_i32_i24_e32 v76, 60, v76
	v_and_b32_e32 v100, 0x1fe00, v78
	v_ashrrev_i32_e32 v77, 31, v76
	v_lshlrev_b64 v[76:77], 17, v[76:77]
	v_lshl_add_u64 v[76:77], s[10:11], 0, v[76:77]
	v_lshl_add_u64 v[76:77], v[76:77], 0, v[100:101]
	v_lshl_add_u64 v[76:77], v[76:77], 0, v[124:125]
	v_lshl_add_u64 v[76:77], v[76:77], 0, v[170:171]
	v_lshrrev_b32_e32 v78, 4, v201
	v_lshlrev_b32_e32 v78, 9, v78
	v_and_b32_e32 v79, 15, v201
	v_lshl_add_u32 v78, v79, 4, v78
	v_lshlrev_b32_e32 v80, 9, v200
	v_sub_u32_e32 v78, v78, v80
	v_lshrrev_b32_e32 v80, 6, v201
	v_lshl_or_b32 v80, v80, 4, v79
	v_lshlrev_b32_e32 v80, 1, v80
	v_sub_u32_e32 v78, v78, v80
	v_ashrrev_i32_e32 v79, 31, v78
	v_lshl_add_u64 v[76:77], v[76:77], 0, v[78:79]
	s_mov_b64 s[48:49], 0x4000
	v_lshl_add_u64 v[78:79], v[76:77], 0, s[48:49]
	global_load_dwordx4 v[184:187], v[76:77], off
	global_load_dwordx4 v[188:191], v[78:79], off
	s_mov_b64 s[48:49], 0
.LBB0_2617:
	s_andn2_b64 vcc, exec, s[48:49]
	s_cbranch_vccnz .LBB0_2620
	s_ashr_i32 s45, s44, 31
	s_lshl_b64 s[4:5], s[44:45], 14
	v_lshl_add_u64 v[52:53], v[168:169], 0, s[4:5]
	s_add_u32 s4, s54, s4
	s_addc_u32 s5, s55, s5
	v_lshl_add_u64 v[54:55], v[116:117], 1, v[52:53]
	s_waitcnt vmcnt(22)
	v_lshl_add_u64 v[56:57], v[120:121], 1, v[52:53]
	v_lshlrev_b32_e32 v80, 1, v208
	v_mov_b32_e32 v81, 0
	v_lshl_add_u64 v[76:77], v[116:117], 1, s[4:5]
	v_lshl_add_u64 v[78:79], v[120:121], 1, s[4:5]
	v_lshl_add_u64 v[76:77], v[76:77], 0, v[80:81]
	v_lshl_add_u64 v[78:79], v[78:79], 0, v[80:81]
	global_load_dwordx4 v[184:187], v[76:77], off
	global_load_dwordx4 v[188:191], v[78:79], off
	s_nop 0
	global_load_dwordx4 v[52:55], v[54:55], off
	s_nop 0
	global_load_dwordx4 v[56:59], v[56:57], off
	s_branch .LBB0_2620

.LBB0_2620:
	s_and_b64 vcc, exec, s[42:43]
	s_cmp_eq_u32 s50, 1
	s_cbranch_scc1 .Lm2_norefill_b
	v_mul_u32_u24_e32 v100, 0x110, v200
	v_lshrrev_b32_e32 v222, 6, v201
	v_and_b32_e32 v238, 15, v201
	v_lshl_or_b32 v222, v222, 4, v238
	v_lshl_add_u32 v100, v222, 1, v100
	v_add_u32_e32 v100, s101, v100
	v_mov_b32_e32 v60, 0
	v_mov_b32_e32 v61, 0
	v_mov_b32_e32 v62, 0
	v_mov_b32_e32 v63, 0
	v_mov_b32_e32 v64, 0
	v_mov_b32_e32 v65, 0
	v_mov_b32_e32 v66, 0
	v_mov_b32_e32 v67, 0
	v_mov_b32_e32 v68, 0
	v_mov_b32_e32 v69, 0
	v_mov_b32_e32 v70, 0
	v_mov_b32_e32 v71, 0
	v_mov_b32_e32 v72, 0
	v_mov_b32_e32 v73, 0
	v_mov_b32_e32 v74, 0
	v_mov_b32_e32 v75, 0
	ds_read_u16_d16_hi v68, v100
	ds_read_u16_d16_hi v69, v100 offset:272
	ds_read_u16_d16_hi v70, v100 offset:544
	ds_read_u16_d16_hi v71, v100 offset:816
	ds_read_u16_d16_hi v72, v100 offset:4352
	ds_read_u16_d16_hi v73, v100 offset:4624
	ds_read_u16_d16_hi v74, v100 offset:4896
	ds_read_u16_d16_hi v75, v100 offset:5168
	ds_read_u16_d16_hi v60, v100 offset:8704
	ds_read_u16_d16_hi v61, v100 offset:8976
	ds_read_u16_d16_hi v62, v100 offset:9248
	ds_read_u16_d16_hi v63, v100 offset:9520
	ds_read_u16_d16_hi v64, v100 offset:13056
	ds_read_u16_d16_hi v65, v100 offset:13328
	ds_read_u16_d16_hi v66, v100 offset:13600
	ds_read_u16_d16_hi v67, v100 offset:13872

.LBB0_2624:
	v_lshl_add_u32 v252, v200, 2, s63
	v_lshl_add_u32 v226, v113, 1, v252
	v_add_u32_e32 v218, v226, v213
	v_add_u32_e32 v222, 0xd000, v218
	v_add_u32_e32 v238, 0x1000, v226
	s_nop 0
	ds_read_b128 v[60:63], v226
	s_nop 0
	ds_read_b128 v[64:67], v226 offset:64
	ds_read_b128 v[68:71], v226 offset:128
	ds_read_b128 v[72:75], v226 offset:192
	ds_read_b128 v[218:221], v222
	ds_read_b128 v[222:225], v222 offset:64
	ds_read_b128 v[226:229], v238 offset:256
	ds_read_b128 v[230:233], v238 offset:320
	ds_read_b128 v[234:237], v238 offset:384
	ds_read_b128 v[238:241], v238 offset:448
	v_add_u32_e32 v253, v252, v115
	v_add_u32_e32 v246, 0xd000, v253
	ds_read_b128 v[242:245], v246
	ds_read_b128 v[246:249], v246 offset:64
	s_cmpk_lt_i32 s64, 0x80
	v_subrev_u32_e32 v100, 32, v126
	s_cselect_b64 vcc, -1, 0
	v_cndmask_b32_e32 v100, v100, v211, vcc
	v_or_b32_e32 v250, v100, v200
	s_waitcnt lgkmcnt(11)
	v_mfma_f32_16x16x32_bf16 v[60:63], v[60:63], v[84:87], 0
	v_ashrrev_i32_e32 v251, 31, v250
	s_waitcnt lgkmcnt(10)
	v_mfma_f32_16x16x32_bf16 v[60:63], v[64:67], v[88:91], v[60:63]
	v_lshlrev_b64 v[64:65], 14, v[250:251]
	s_waitcnt lgkmcnt(9)
	v_mfma_f32_16x16x32_bf16 v[60:63], v[68:71], v[92:95], v[60:63]
	v_lshl_add_u64 v[68:69], v[182:183], 0, v[64:65]
	v_add_co_u32_e64 v70, s[4:5], s58, v68
	s_waitcnt lgkmcnt(5)
	v_mfma_f32_16x16x32_bf16 v[226:229], v[226:229], v[84:87], 0
	v_addc_co_u32_e64 v71, s[4:5], 0, v69, s[4:5]
	v_mfma_f32_16x16x32_bf16 v[60:63], v[72:75], v[96:99], v[60:63]
	v_mfma_f32_16x16x32_bf16 v[60:63], v[218:221], v[76:79], v[60:63]
	s_waitcnt lgkmcnt(4)
	v_mfma_f32_16x16x32_bf16 v[64:67], v[230:233], v[88:91], v[226:229]
	v_mfma_f32_16x16x32_bf16 v[60:63], v[222:225], v[80:83], v[60:63]
	s_waitcnt lgkmcnt(3)
	v_mfma_f32_16x16x32_bf16 v[64:67], v[234:237], v[92:95], v[64:67]
	s_waitcnt lgkmcnt(2)
	v_mfma_f32_16x16x32_bf16 v[64:67], v[238:241], v[96:99], v[64:67]
	s_nop 3
	global_store_dword v[68:69], v60, off
	v_add_co_u32_e64 v60, s[4:5], s59, v68
	global_store_dword v[70:71], v61, off
	s_nop 0
	v_addc_co_u32_e64 v61, s[4:5], 0, v69, s[4:5]
	global_store_dword v[60:61], v62, off
	v_add_co_u32_e64 v60, s[4:5], s60, v68
	v_or_b32_e32 v68, 16, v250
	s_nop 0
	v_addc_co_u32_e64 v61, s[4:5], 0, v69, s[4:5]
	global_store_dword v[60:61], v63, off
	s_waitcnt lgkmcnt(1)
	v_mfma_f32_16x16x32_bf16 v[60:63], v[242:245], v[76:79], v[64:67]
	v_ashrrev_i32_e32 v69, 31, v68
	s_nop 1
	v_lshlrev_b64 v[64:65], 14, v[68:69]
	s_waitcnt lgkmcnt(0)
	v_mfma_f32_16x16x32_bf16 v[60:63], v[246:249], v[80:83], v[60:63]
	v_lshl_add_u64 v[64:65], v[182:183], 0, v[64:65]
	v_add_co_u32_e64 v66, s[4:5], s58, v64
	s_nop 1
	v_addc_co_u32_e64 v67, s[4:5], 0, v65, s[4:5]
	s_nop 2
	global_store_dword v[64:65], v60, off
	v_add_co_u32_e64 v60, s[4:5], s59, v64
	global_store_dword v[66:67], v61, off
	s_nop 0
	v_addc_co_u32_e64 v61, s[4:5], 0, v65, s[4:5]
	global_store_dword v[60:61], v62, off
	v_add_co_u32_e64 v60, s[4:5], s60, v64
	s_nop 1
	v_addc_co_u32_e64 v61, s[4:5], 0, v65, s[4:5]
	global_store_dword v[60:61], v63, off
	v_add_u32_e32 v100, v252, v212
	v_add_u32_e32 v218, v100, v217
	ds_read_b128 v[60:63], v100
	ds_read_b128 v[64:67], v100 offset:64
	ds_read_b128 v[68:71], v100 offset:128
	ds_read_b128 v[72:75], v100 offset:192
	v_add_u32_e32 v222, 0xd000, v218
	v_add_u32_e32 v100, 0x1000, v100
	ds_read_b128 v[218:221], v222
	ds_read_b128 v[222:225], v222 offset:64
	ds_read_b128 v[226:229], v100 offset:256
	ds_read_b128 v[230:233], v100 offset:320
	ds_read_b128 v[234:237], v100 offset:384
	ds_read_b128 v[238:241], v100 offset:448
	v_add_u32_e32 v100, 0xe000, v253
	ds_read_b128 v[242:245], v100 offset:512
	ds_read_b128 v[246:249], v100 offset:576
	s_waitcnt lgkmcnt(11)
	v_mfma_f32_16x16x32_bf16 v[60:63], v[60:63], v[84:87], 0
	s_waitcnt lgkmcnt(10)
	v_mfma_f32_16x16x32_bf16 v[60:63], v[64:67], v[88:91], v[60:63]
	v_add_u32_e32 v64, 32, v250
	v_ashrrev_i32_e32 v65, 31, v64
	v_lshlrev_b64 v[64:65], 14, v[64:65]
	s_waitcnt lgkmcnt(9)
	v_mfma_f32_16x16x32_bf16 v[60:63], v[68:71], v[92:95], v[60:63]
	v_lshl_add_u64 v[64:65], v[182:183], 0, v[64:65]
	v_cndmask_b32_e32 v69, v179, v65, vcc
	v_cndmask_b32_e32 v68, v178, v64, vcc
	s_waitcnt lgkmcnt(8)
	v_mfma_f32_16x16x32_bf16 v[60:63], v[72:75], v[96:99], v[60:63]
	v_add_co_u32_e64 v70, s[4:5], s58, v68
	s_waitcnt lgkmcnt(7)
	v_mfma_f32_16x16x32_bf16 v[60:63], v[218:221], v[76:79], v[60:63]
	v_addc_co_u32_e64 v71, s[4:5], 0, v69, s[4:5]
	s_waitcnt lgkmcnt(5)
	v_mfma_f32_16x16x32_bf16 v[64:67], v[226:229], v[84:87], 0
	v_mfma_f32_16x16x32_bf16 v[60:63], v[222:225], v[80:83], v[60:63]
	s_waitcnt lgkmcnt(4)
	v_mfma_f32_16x16x32_bf16 v[64:67], v[230:233], v[88:91], v[64:67]
	s_waitcnt lgkmcnt(3)
	v_mfma_f32_16x16x32_bf16 v[64:67], v[234:237], v[92:95], v[64:67]
	s_nop 3
	global_store_dword v[68:69], v60, off
	v_add_co_u32_e64 v60, s[4:5], s59, v68
	global_store_dword v[70:71], v61, off
	s_nop 0
	v_addc_co_u32_e64 v61, s[4:5], 0, v69, s[4:5]
	global_store_dword v[60:61], v62, off
	v_add_co_u32_e64 v60, s[4:5], s60, v68
	s_nop 1
	v_addc_co_u32_e64 v61, s[4:5], 0, v69, s[4:5]
	global_store_dword v[60:61], v63, off
	s_waitcnt lgkmcnt(2)
	v_mfma_f32_16x16x32_bf16 v[60:63], v[238:241], v[96:99], v[64:67]
	s_waitcnt lgkmcnt(1)
	v_mfma_f32_16x16x32_bf16 v[60:63], v[242:245], v[76:79], v[60:63]
	s_nop 0
	v_add_u32_e32 v64, 48, v250
	v_ashrrev_i32_e32 v65, 31, v64
	v_lshlrev_b64 v[64:65], 14, v[64:65]
	v_lshl_add_u64 v[64:65], v[182:183], 0, v[64:65]
	s_waitcnt lgkmcnt(0)
	v_mfma_f32_16x16x32_bf16 v[60:63], v[246:249], v[80:83], v[60:63]
	v_cndmask_b32_e32 v64, v180, v64, vcc
	v_cndmask_b32_e32 v65, v181, v65, vcc
	v_add_co_u32_e32 v66, vcc, s58, v64
	s_nop 1
	v_addc_co_u32_e32 v67, vcc, 0, v65, vcc
	s_nop 1
	global_store_dword v[64:65], v60, off
	v_add_co_u32_e32 v60, vcc, s59, v64
	global_store_dword v[66:67], v61, off
	s_nop 0
	v_addc_co_u32_e32 v61, vcc, 0, v65, vcc
	global_store_dword v[60:61], v62, off
	v_add_co_u32_e32 v60, vcc, s60, v64
	s_nop 1
	v_addc_co_u32_e32 v61, vcc, 0, v65, vcc
	global_store_dword v[60:61], v63, off
	v_lshl_add_u32 v100, v200, 2, s63
	v_add_u32_e32 v234, v100, v103
	v_add_u32_e32 v64, 0x8800, v234
	v_add_u32_e32 v88, 0x9000, v234
	v_add_u32_e32 v96, 0x9800, v234
	ds_read_b128 v[60:63], v64
	ds_read_b128 v[64:67], v64 offset:64
	ds_read_b128 v[68:71], v100 offset:62464
	ds_read_b128 v[72:75], v100 offset:62528
	ds_read_b128 v[84:87], v88 offset:256
	ds_read_b128 v[88:91], v88 offset:320
	ds_read_b128 v[92:95], v96 offset:512
	ds_read_b128 v[96:99], v96 offset:576
	ds_read_b128 v[218:221], v100 offset:62592
	ds_read_b128 v[222:225], v100 offset:62656
	v_add_u32_e32 v230, 0xa000, v234
	ds_read_b128 v[226:229], v230 offset:768
	ds_read_b128 v[230:233], v230 offset:832
	s_waitcnt lgkmcnt(9)
	v_pk_mul_f32 v[2:3], v[2:3], v[70:71]
	v_pk_mul_f32 v[0:1], v[0:1], v[68:69]
	s_waitcnt lgkmcnt(8)
	v_pk_mul_f32 v[6:7], v[6:7], v[74:75]
	v_pk_mul_f32 v[4:5], v[4:5], v[72:73]
	s_waitcnt lgkmcnt(3)
	v_pk_mul_f32 v[10:11], v[10:11], v[220:221]
	v_pk_mul_f32 v[8:9], v[8:9], v[218:219]
	s_waitcnt lgkmcnt(2)
	v_pk_mul_f32 v[14:15], v[14:15], v[224:225]
	v_pk_mul_f32 v[12:13], v[12:13], v[222:223]
	v_mfma_f32_16x16x32_bf16 v[0:3], v[60:63], v[76:79], v[0:3]
	v_mfma_f32_16x16x32_bf16 v[4:7], v[84:87], v[76:79], v[4:7]
	v_mfma_f32_16x16x32_bf16 v[8:11], v[92:95], v[76:79], v[8:11]
	s_waitcnt lgkmcnt(1)
	v_mfma_f32_16x16x32_bf16 v[12:15], v[226:229], v[76:79], v[12:15]
	v_mfma_f32_16x16x32_bf16 v[0:3], v[64:67], v[80:83], v[0:3]
	v_mfma_f32_16x16x32_bf16 v[4:7], v[88:91], v[80:83], v[4:7]
	v_mfma_f32_16x16x32_bf16 v[8:11], v[96:99], v[80:83], v[8:11]
	s_waitcnt lgkmcnt(0)
	v_mfma_f32_16x16x32_bf16 v[12:15], v[230:233], v[80:83], v[12:15]
	v_add_u32_e32 v64, 0xa800, v234
	v_add_u32_e32 v88, 0xb000, v234
	v_add_u32_e32 v96, 0xb800, v234
	ds_read_b128 v[60:63], v64 offset:1024
	ds_read_b128 v[64:67], v64 offset:1088
	ds_read_b128 v[68:71], v100 offset:62720
	ds_read_b128 v[72:75], v100 offset:62784
	ds_read_b128 v[84:87], v88 offset:1280
	ds_read_b128 v[88:91], v88 offset:1344
	ds_read_b128 v[92:95], v96 offset:1536
	ds_read_b128 v[96:99], v96 offset:1600
	ds_read_b128 v[218:221], v100 offset:62848
	ds_read_b128 v[222:225], v100 offset:62912
	v_add_u32_e32 v100, 0xc000, v234
	ds_read_b128 v[226:229], v100 offset:1792
	ds_read_b128 v[230:233], v100 offset:1856
	s_waitcnt lgkmcnt(9)
	v_pk_mul_f32 v[18:19], v[18:19], v[70:71]
	v_pk_mul_f32 v[16:17], v[16:17], v[68:69]
	s_waitcnt lgkmcnt(8)
	v_pk_mul_f32 v[22:23], v[22:23], v[74:75]
	v_pk_mul_f32 v[20:21], v[20:21], v[72:73]
	s_waitcnt lgkmcnt(3)
	v_pk_mul_f32 v[26:27], v[26:27], v[220:221]
	v_pk_mul_f32 v[24:25], v[24:25], v[218:219]
	s_waitcnt lgkmcnt(2)
	v_pk_mul_f32 v[30:31], v[30:31], v[224:225]
	v_pk_mul_f32 v[28:29], v[28:29], v[222:223]
	v_mfma_f32_16x16x32_bf16 v[16:19], v[60:63], v[76:79], v[16:19]
	v_mfma_f32_16x16x32_bf16 v[20:23], v[84:87], v[76:79], v[20:23]
	v_mfma_f32_16x16x32_bf16 v[24:27], v[92:95], v[76:79], v[24:27]
	s_waitcnt lgkmcnt(1)
	v_mfma_f32_16x16x32_bf16 v[28:31], v[226:229], v[76:79], v[28:31]
	v_mfma_f32_16x16x32_bf16 v[16:19], v[64:67], v[80:83], v[16:19]
	v_mfma_f32_16x16x32_bf16 v[20:23], v[88:91], v[80:83], v[20:23]
	v_mfma_f32_16x16x32_bf16 v[24:27], v[96:99], v[80:83], v[24:27]
	s_waitcnt lgkmcnt(0)
	v_mfma_f32_16x16x32_bf16 v[28:31], v[230:233], v[80:83], v[28:31]
	s_add_i32 s53, s53, 16
	s_add_i32 s22, s22, 28
	v_add_u32_e32 v126, 32, v126
	s_cmp_lg_u32 s51, s50
	v_add_u32_e32 v211, 64, v211
	s_cbranch_scc0 .LBB0_2517
	s_waitcnt vmcnt(16)
	s_branch .LBB0_2604

	.amdhsa_kernel _Z3fwd4Args
		.amdhsa_group_segment_fixed_size 0
		.amdhsa_private_segment_fixed_size 0
		.amdhsa_kernarg_size 512
		.amdhsa_user_sgpr_count 2
		.amdhsa_user_sgpr_dispatch_ptr 0
		.amdhsa_user_sgpr_queue_ptr 0
		.amdhsa_user_sgpr_kernarg_segment_ptr 1
		.amdhsa_user_sgpr_dispatch_id 0
		.amdhsa_user_sgpr_kernarg_preload_length 0
		.amdhsa_user_sgpr_kernarg_preload_offset 0
		.amdhsa_user_sgpr_private_segment_size 0
		.amdhsa_uses_dynamic_stack 0
		.amdhsa_enable_private_segment 0
		.amdhsa_system_sgpr_workgroup_id_x 1
		.amdhsa_system_sgpr_workgroup_id_y 0
		.amdhsa_system_sgpr_workgroup_id_z 0
		.amdhsa_system_sgpr_workgroup_info 0
		.amdhsa_system_vgpr_workitem_id 0
		.amdhsa_next_free_vgpr 256
		.amdhsa_next_free_sgpr 102
		.amdhsa_accum_offset 256
		.amdhsa_reserve_vcc 1
		.amdhsa_float_round_mode_32 0
		.amdhsa_float_round_mode_16_64 0
		.amdhsa_float_denorm_mode_32 3
		.amdhsa_float_denorm_mode_16_64 3
		.amdhsa_dx10_clamp 1
		.amdhsa_ieee_mode 1
		.amdhsa_fp16_overflow 0
		.amdhsa_tg_split 0
		.amdhsa_exception_fp_ieee_invalid_op 0
		.amdhsa_exception_fp_denorm_src 0
		.amdhsa_exception_fp_ieee_div_zero 0
		.amdhsa_exception_fp_ieee_overflow 0
		.amdhsa_exception_fp_ieee_underflow 0
		.amdhsa_exception_fp_ieee_inexact 0
		.amdhsa_exception_int_div_zero 0
	.end_amdhsa_kernel

amdhsa.kernels:
  - .agpr_count:     0
    .args:
      - .offset:         0
        .size:           256
        .value_kind:     by_value
      - .offset:         256
        .size:           4
        .value_kind:     hidden_block_count_x
      - .offset:         260
        .size:           4
        .value_kind:     hidden_block_count_y
      - .offset:         264
        .size:           4
        .value_kind:     hidden_block_count_z
      - .offset:         268
        .size:           2
        .value_kind:     hidden_group_size_x
      - .offset:         270
        .size:           2
        .value_kind:     hidden_group_size_y
      - .offset:         272
        .size:           2
        .value_kind:     hidden_group_size_z
      - .offset:         274
        .size:           2
        .value_kind:     hidden_remainder_x
      - .offset:         276
        .size:           2
        .value_kind:     hidden_remainder_y
      - .offset:         278
        .size:           2
        .value_kind:     hidden_remainder_z
      - .offset:         296
        .size:           8
        .value_kind:     hidden_global_offset_x
      - .offset:         304
        .size:           8
        .value_kind:     hidden_global_offset_y
      - .offset:         312
        .size:           8
        .value_kind:     hidden_global_offset_z
      - .offset:         320
        .size:           2
        .value_kind:     hidden_grid_dims
      - .offset:         376
        .size:           4
        .value_kind:     hidden_dynamic_lds_size
    .group_segment_fixed_size: 0
    .kernarg_segment_align: 8
    .kernarg_segment_size: 512
    .language:       OpenCL C
    .language_version:
      - 2
      - 0
    .max_flat_workgroup_size: 512
    .name:           _Z3fwd4Args
    .private_segment_fixed_size: 0
    .sgpr_count:     108
    .sgpr_spill_count: 150
    .symbol:         _Z3fwd4Args.kd
    .uniform_work_group_size: 1
    .uses_dynamic_stack: false
    .vgpr_count:     256
    .vgpr_spill_count: 0
    .wavefront_size: 64
